# v15stg5
# baseline (speedup 1.0000x reference)
.LBB0_25:
	s_lshr_b32 s6, s2, 7
	s_and_b32 s6, s6, 1
	s_cmp_eq_u32 s6, 0
	s_cbranch_scc1 .Lstg_done
	s_mov_b32 s7, 0
	s_cmp_eq_u32 s3, 1
	s_cselect_b32 s7, 0, s7
	s_cmp_eq_u32 s3, 3
	s_cselect_b32 s7, 0, s7
	s_cmp_eq_u32 s3, 4
	s_cselect_b32 s7, 0, s7
	s_cmp_eq_u32 s3, 5
	s_cselect_b32 s7, 400, s7
	s_cmp_eq_u32 s3, 6
	s_cselect_b32 s7, 0, s7
	s_cmp_eq_u32 s7, 0
	s_cbranch_scc1 .Lstg_done
	s_memrealtime s[12:13]
	s_waitcnt lgkmcnt(0)
.Lstg_loop:
	s_sleep 8
	s_memrealtime s[76:77]
	s_waitcnt lgkmcnt(0)
	s_sub_u32 s6, s76, s12
	s_cmp_lt_u32 s6, s7
	s_cbranch_scc1 .Lstg_loop
